# attention PV section (both unrolled key tiles): V fragment LDS reads prefetched ahead into v242-v253 instead of serialized read-wait-mfma; on top of v50
# speedup vs baseline: 1.0096x; 1.0009x over previous
; #define MFMA16(a, b, c) __builtin_amdgcn_mfma_f32_16x16x32_bf16((a), (b), (c), 0, 0, 0)
; __device__ __forceinline__ void attn_unit(const WS& ws, int u, bool dry = false) {
;     ...
;       const float mnew = mrun[nt];
;       float ps = 0.f;
; #pragma unroll
;       for (int mt = 0; mt < 4; ++mt)
; #pragma unroll
;         for (int jj = 0; jj < 4; ++jj) { const float pv = __builtin_amdgcn_exp2f(s[mt][nt][jj] - mnew); s[mt][nt][jj] = pv; ps += pv; }
;       lsum[nt] += ps;
; #pragma unroll
;       for (int ks = 0; ks < 2; ++ks) {
;         u32x4 pk;
;         pk.x = cvt_pk_bf16(s[2 * ks][nt][0], s[2 * ks][nt][1]); pk.y = cvt_pk_bf16(s[2 * ks][nt][2], s[2 * ks][nt][3]);
;         pk.z = cvt_pk_bf16(s[2 * ks + 1][nt][0], s[2 * ks + 1][nt][1]); pk.w = cvt_pk_bf16(s[2 * ks + 1][nt][2], s[2 * ks + 1][nt][3]);
;         pf[nt][ks] = as_bf16x8(pk);
;       }
;     }
; #pragma unroll
;     for (int mt = 0; mt < 4; ++mt)
; #pragma unroll
;       for (int ks = 0; ks < 2; ++ks) {
;         const u32x2 lo = *(const u32x2*)(Vb + (16 * mt + lr) * 72 + 32 * ks + 4 * lq);
;         const u32x2 hi = *(const u32x2*)(Vb + (16 * mt + lr) * 72 + 32 * ks + 16 + 4 * lq);
;         const bf16x8 vf = as_bf16x8((u32x4){lo.x, lo.y, hi.x, hi.y});
;         oacc[mt][0] = MFMA16(vf, pf[0][ks], oacc[mt][0]);
;         oacc[mt][1] = MFMA16(vf, pf[1][ks], oacc[mt][1]);
;       }
;     stores(buf ^ 1, kregn, vregn);
;     __syncthreads();
;   };
; #pragma unroll 1
;   for (int kt = 0; kt < nkt2; kt += 2) {
;     body(kt, 0, kregA, vregA, kregB, vregB);
;     body(kt + 1, 1, kregB, vregB, kregA, vregA);
;   }
.LBB0_877:
	v_sub_f32_e32 v90, v126, v204
	v_exp_f32_e32 v90, v90
	v_sub_f32_e32 v92, v127, v204
	v_exp_f32_e32 v92, v92
	v_sub_f32_e32 v93, v128, v204
	v_exp_f32_e32 v93, v93
	v_sub_f32_e32 v94, v129, v204
	v_exp_f32_e32 v94, v94
	v_sub_f32_e32 v95, v122, v204
	v_add_f32_e32 v91, 0, v90
	v_exp_f32_e32 v95, v95
	v_sub_f32_e32 v96, v123, v204
	v_add_f32_e32 v91, v92, v91
	v_exp_f32_e32 v96, v96
	v_sub_f32_e32 v97, v124, v204
	v_add_f32_e32 v91, v93, v91
	v_exp_f32_e32 v97, v97
	v_sub_f32_e32 v98, v125, v204
	v_add_f32_e32 v91, v94, v91
	v_exp_f32_e32 v109, v98
	v_sub_f32_e32 v98, v118, v204
	v_add_f32_e32 v91, v95, v91
	v_exp_f32_e32 v98, v98
	v_sub_f32_e32 v99, v119, v204
	v_add_f32_e32 v91, v96, v91
	v_exp_f32_e32 v99, v99
	v_sub_f32_e32 v100, v120, v204
	v_add_f32_e32 v91, v97, v91
	v_exp_f32_e32 v100, v100
	v_sub_f32_e32 v101, v121, v204
	v_add_f32_e32 v91, v109, v91
	v_exp_f32_e32 v101, v101
	v_sub_f32_e32 v106, v114, v204
	v_sub_f32_e32 v107, v115, v204
	v_sub_f32_e32 v34, v34, v203
	v_add_f32_e32 v91, v98, v91
	v_exp_f32_e32 v106, v106
	v_exp_f32_e32 v107, v107
	v_exp_f32_e32 v34, v34
	v_sub_f32_e32 v35, v35, v203
	v_add_f32_e32 v91, v99, v91
	v_exp_f32_e32 v35, v35
	v_sub_f32_e32 v36, v36, v203
	v_add_f32_e32 v91, v100, v91
	v_exp_f32_e32 v36, v36
	v_sub_f32_e32 v37, v37, v203
	v_add_f32_e32 v91, v101, v91
	v_exp_f32_e32 v37, v37
	v_sub_f32_e32 v38, v38, v203
	v_add_f32_e32 v91, v106, v91
	v_cvt_pk_bf16_f32 v98, v98, v99
	v_cvt_pk_bf16_f32 v99, v100, v101
	v_cvt_pk_bf16_f32 v100, v106, v107
	v_cvt_pk_bf16_f32 v106, v90, v92
	v_add_f32_e32 v90, 0, v34
	v_exp_f32_e32 v38, v38
	v_sub_f32_e32 v39, v39, v203
	v_add_f32_e32 v90, v35, v90
	v_exp_f32_e32 v39, v39
	v_sub_f32_e32 v40, v40, v203
	v_add_f32_e32 v90, v36, v90
	v_exp_f32_e32 v40, v40
	v_sub_f32_e32 v41, v41, v203
	v_add_f32_e32 v90, v37, v90
	v_exp_f32_e32 v41, v41
	v_sub_f32_e32 v46, v46, v203
	v_add_f32_e32 v90, v38, v90
	v_exp_f32_e32 v46, v46
	v_sub_f32_e32 v47, v47, v203
	v_add_f32_e32 v90, v39, v90
	v_exp_f32_e32 v47, v47
	v_sub_f32_e32 v48, v48, v203
	v_add_f32_e32 v90, v40, v90
	v_exp_f32_e32 v48, v48
	v_sub_f32_e32 v49, v49, v203
	v_add_f32_e32 v90, v41, v90
	v_exp_f32_e32 v49, v49
	v_sub_f32_e32 v62, v62, v203
	v_sub_f32_e32 v63, v63, v203
	v_add_f32_e32 v90, v46, v90
	v_exp_f32_e32 v62, v62
	v_exp_f32_e32 v63, v63
	v_add_f32_e32 v90, v47, v90
	v_add_f32_e32 v90, v48, v90
	v_add_f32_e32 v90, v49, v90
	v_sub_f32_e32 v64, v64, v203
	v_add_f32_e32 v90, v62, v90
	v_exp_f32_e32 v64, v64
	v_sub_f32_e32 v65, v65, v203
	v_cvt_pk_bf16_f32 v115, v36, v37
	v_cvt_pk_bf16_f32 v36, v62, v63
	v_add_u32_e32 v62, 0x8800, v184
	v_sub_f32_e32 v108, v116, v204
	v_sub_f32_e32 v114, v117, v204
	v_exp_f32_e32 v65, v65
	v_cvt_pk_bf16_f32 v116, v38, v39
	v_cvt_pk_bf16_f32 v117, v40, v41
	ds_read2_b64 v[38:41], v62 offset0:128 offset1:132
	v_add_f32_e32 v90, v63, v90
	v_exp_f32_e32 v108, v108
	v_add_f32_e32 v90, v64, v90
	v_exp_f32_e32 v114, v114
	v_add_f32_e32 v90, v65, v90
	v_cvt_pk_bf16_f32 v37, v64, v65
	ds_read2_b64 v[62:65], v62 offset0:136 offset1:140
	v_add_f32_e32 v91, v107, v91
	v_add_f32_e32 v91, v108, v91
	v_add_f32_e32 v91, v114, v91
	v_cvt_pk_bf16_f32 v101, v108, v114
	v_cvt_pk_bf16_f32 v107, v93, v94
	v_cvt_pk_bf16_f32 v108, v95, v96
	v_cvt_pk_bf16_f32 v109, v97, v109
	v_cvt_pk_bf16_f32 v114, v34, v35
	v_cvt_pk_bf16_f32 v34, v46, v47
	v_cvt_pk_bf16_f32 v35, v48, v49
	s_waitcnt lgkmcnt(1)
	v_mfma_f32_16x16x32_bf16 v[46:49], v[38:41], v[106:109], v[110:113]
	v_add_f32_e32 v176, v176, v90
	v_add_u32_e32 v90, 0x9000, v184
	v_add_u32_e32 v254, 0x9800, v184
	v_add_u32_e32 v255, 0xa000, v184
	ds_read2_b64 v[242:245], v90 offset0:160 offset1:164
	ds_read2_b64 v[246:249], v90 offset0:168 offset1:172
	ds_read2_b64 v[250:253], v254 offset0:192 offset1:196
	v_add_f32_e32 v201, v201, v91
	v_mfma_f32_16x16x32_bf16 v[38:41], v[38:41], v[114:117], v[142:145]
	v_or_b32_e32 v91, s6, v174
	v_cmp_lt_i32_e32 vcc, s16, v91
	v_or_b32_e32 v91, s4, v174
	s_waitcnt lgkmcnt(3)
	v_mfma_f32_16x16x32_bf16 v[94:97], v[62:65], v[98:101], v[46:49]
	s_waitcnt vmcnt(1)
	v_cndmask_b32_e64 v73, v73, 0, vcc
	v_cndmask_b32_e64 v72, v72, 0, vcc
	v_cndmask_b32_e64 v71, v71, 0, vcc
	v_mfma_f32_16x16x32_bf16 v[62:65], v[62:65], v[34:37], v[38:41]
	v_cndmask_b32_e64 v70, v70, 0, vcc
	s_waitcnt vmcnt(0)
	v_cndmask_b32_e64 v81, v81, 0, vcc
	v_cndmask_b32_e64 v80, v80, 0, vcc
	s_waitcnt lgkmcnt(2)
	v_mfma_f32_16x16x32_bf16 v[46:49], v[242:245], v[106:109], v[102:105]
	s_nop 2
	v_cndmask_b32_e64 v79, v79, 0, vcc
	v_cndmask_b32_e64 v78, v78, 0, vcc
	v_mfma_f32_16x16x32_bf16 v[38:41], v[242:245], v[114:117], v[138:141]
	ds_read2_b64 v[242:245], v254 offset0:200 offset1:204
	v_cmp_lt_i32_e32 vcc, s16, v91
	v_add_u32_e32 v110, 0xa000, v184
	s_add_i32 s35, s35, 2
	s_waitcnt lgkmcnt(2)
	v_mfma_f32_16x16x32_bf16 v[90:93], v[246:249], v[98:101], v[46:49]
	s_add_i32 s5, s5, 1
	v_add_u32_e32 v185, 0x80, v185
	s_cmp_ge_u32 s5, s36
	v_mfma_f32_16x16x32_bf16 v[46:49], v[246:249], v[34:37], v[38:41]
	ds_read2_b64 v[246:249], v255 offset0:224 offset1:228
	v_add_u32_e32 v102, 0x9800, v184
	v_cndmask_b32_e64 v89, v89, 0, vcc
	v_cndmask_b32_e64 v88, v88, 0, vcc
	s_waitcnt lgkmcnt(2)
	v_mfma_f32_16x16x32_bf16 v[74:77], v[250:253], v[106:109], v[74:77]
	v_cndmask_b32_e64 v87, v87, 0, vcc
	v_cndmask_b32_e64 v86, v86, 0, vcc
	v_cndmask_b32_e64 v85, v85, 0, vcc
	v_mfma_f32_16x16x32_bf16 v[38:41], v[250:253], v[114:117], v[134:137]
	ds_read2_b64 v[250:253], v255 offset0:232 offset1:236
	v_cndmask_b32_e64 v84, v84, 0, vcc
	v_cndmask_b32_e64 v83, v83, 0, vcc
	v_cndmask_b32_e64 v82, v82, 0, vcc
	s_waitcnt lgkmcnt(2)
	v_mfma_f32_16x16x32_bf16 v[74:77], v[242:245], v[98:101], v[74:77]
	v_mfma_f32_16x16x32_bf16 v[38:41], v[242:245], v[34:37], v[38:41]
	s_waitcnt lgkmcnt(1)
	v_mfma_f32_16x16x32_bf16 v[66:69], v[246:249], v[106:109], v[66:69]
	ds_write_b128 v177, v[50:53]
	ds_write_b128 v178, v[54:57]
	ds_write_b128 v179, v[58:61]
	ds_write_b128 v180, v[86:89] offset:26624
	ds_write_b128 v181, v[82:85] offset:26624
	s_waitcnt lgkmcnt(0)
	v_mfma_f32_16x16x32_bf16 v[102:105], v[246:249], v[114:117], v[130:133]
	s_barrier
	v_mfma_f32_16x16x32_bf16 v[66:69], v[250:253], v[98:101], v[66:69]
	v_mfma_f32_16x16x32_bf16 v[34:37], v[250:253], v[34:37], v[102:105]
	s_cbranch_scc1 .LBB0_881
	v_mov_b32_e32 v202, v203
	v_mov_b32_e32 v203, v204
	s_branch .LBB0_863
